# NSA unit: running out_b total kept in registers across compressed/selected/window branches (no read-modify-write round trips)
# speedup vs baseline: 1.0225x; 1.0158x over previous
; DI unsigned cvtpk(float lo, float hi) { return pg8::cvt_pk_bf16(lo, hi); }
; DI float bflo(unsigned w) { return __uint_as_float(w << 16); }
; DI float bfhi(unsigned w) { return __uint_as_float(w & 0xffff0000u); }
; template <bool FIRST> DI void attn_flush(const AttnSt& st, const float (&sc)[NRT], bf16_t* const (&orow)[NRT]) {
;     ...
;     for (int rt = 0; rt < NRT; ++rt) { u32x2 old[2][4];
;         if (!FIRST) {
; #pragma unroll
;             for (int dt = 0; dt < 2; ++dt)
; #pragma unroll
;                 for (int q4 = 0; q4 < 4; ++q4) old[dt][q4] = *(const u32x2*)(orow[rt] + dt * 32 + 8 * q4); }
; #pragma unroll
;         for (int dt = 0; dt < 2; ++dt)
; #pragma unroll
;             for (int q4 = 0; q4 < 4; ++q4) { u32x2* p = (u32x2*)(orow[rt] + dt * 32 + 8 * q4); float v0 = st.o[dt][rt][4 * q4] * sc[rt], v1 = st.o[dt][rt][4 * q4 + 1] * sc[rt], v2 = st.o[dt][rt][4 * q4 + 2] * sc[rt], v3 = st.o[dt][rt][4 * q4 + 3] * sc[rt];
;                 if (!FIRST) { v0 += bflo(old[dt][q4].x); v1 += bfhi(old[dt][q4].x); v2 += bflo(old[dt][q4].y); v3 += bfhi(old[dt][q4].y); }
;                 u32x2 w; w.x = cvtpk(v0, v1); w.y = cvtpk(v2, v3); *p = w; } }
; DI void nsa_wg_unit(const Args& a, int l, int b, int g, int tb, unsigned char* lds, int tid_in, bool stage) {
;     ...
;     { float sc[NRT]; const float lt = st.l[0] + __shfl_xor(st.l[0], 32); sc[0] = lt > 0.f ? gt[0][2] / lt : 0.f; attn_flush<false>(st, sc, orow); }
.LBB0_111:
	v_lshlrev_b32_e32 v32, 16, v139
	v_mul_f32_e32 v32, 0xbfb8aa3b, v32
	ds_bpermute_b32 v165, v148, v137
	v_exp_f32_e32 v136, v32
	v_readlane_b32 s2, v253, 34
	s_movk_i32 s93, 0x5ff
	s_waitcnt lgkmcnt(0)
	v_pk_add_f32 v[32:33], v[136:137], v[164:165]
	s_nop 0
	v_div_scale_f32 v34, s[0:1], v32, v32, 1.0
	v_rcp_f32_e32 v35, v34
	v_cmp_lt_f32_e64 s[6:7], 0, v33
	v_fma_f32 v36, -v34, v35, 1.0
	v_fmac_f32_e32 v35, v36, v35
	v_div_scale_f32 v36, vcc, 1.0, v32, 1.0
	v_mul_f32_e32 v37, v36, v35
	v_fma_f32 v38, -v34, v37, v36
	v_fmac_f32_e32 v37, v38, v35
	v_fma_f32 v34, -v34, v37, v36
	v_div_fmas_f32 v34, v34, v35, v37
	v_div_fixup_f32 v32, v34, v32, 1.0
	v_div_scale_f32 v34, s[0:1], v33, v33, v32
	v_rcp_f32_e32 v35, v34
	s_nop 0
	v_fma_f32 v36, -v34, v35, 1.0
	v_fmac_f32_e32 v35, v36, v35
	v_div_scale_f32 v36, vcc, v32, v33, v32
	v_mul_f32_e32 v37, v36, v35
	v_fma_f32 v38, -v34, v37, v36
	v_fmac_f32_e32 v37, v38, v35
	v_fma_f32 v34, -v34, v37, v36
	v_div_fmas_f32 v34, v34, v35, v37
	v_div_fixup_f32 v32, v34, v33, v32
	v_mov_b64_e32 v[44:45], v[236:237]
	v_mov_b64_e32 v[46:47], v[238:239]
	v_mov_b64_e32 v[48:49], v[240:241]
	v_mov_b64_e32 v[42:43], v[242:243]
	v_mov_b64_e32 v[40:41], v[244:245]
	v_mov_b64_e32 v[38:39], v[246:247]
	v_mov_b64_e32 v[36:37], v[248:249]
	v_mov_b64_e32 v[34:35], v[250:251]
	v_cndmask_b32_e64 v32, 0, v32, s[6:7]
	v_readlane_b32 s7, v254, 50
	s_add_i32 s7, s7, s52
	s_cmpk_gt_i32 s7, 0x1ff
	s_waitcnt vmcnt(7)
	v_lshlrev_b32_e32 v50, 16, v44
	v_and_b32_e32 v51, 0xffff0000, v44
	v_lshlrev_b32_e32 v44, 16, v45
	v_and_b32_e32 v45, 0xffff0000, v45
	v_pk_fma_f32 v[16:17], v[16:17], v[32:33], v[50:51] op_sel_hi:[1,0,1]
	v_pk_fma_f32 v[18:19], v[18:19], v[32:33], v[44:45] op_sel_hi:[1,0,1]
	v_cvt_pk_bf16_f32 v16, v16, v17
	v_cvt_pk_bf16_f32 v17, v18, v19
	global_store_dwordx2 v[140:141], v[16:17], off
	s_waitcnt vmcnt(7)
	v_lshlrev_b32_e32 v16, 16, v46
	v_and_b32_e32 v17, 0xffff0000, v46
	v_lshlrev_b32_e32 v18, 16, v47
	v_and_b32_e32 v19, 0xffff0000, v47
	v_pk_fma_f32 v[16:17], v[20:21], v[32:33], v[16:17] op_sel_hi:[1,0,1]
	v_pk_fma_f32 v[18:19], v[22:23], v[32:33], v[18:19] op_sel_hi:[1,0,1]
	v_cvt_pk_bf16_f32 v16, v16, v17
	v_cvt_pk_bf16_f32 v17, v18, v19
	global_store_dwordx2 v[140:141], v[16:17], off offset:16
	s_waitcnt vmcnt(7)
	v_lshlrev_b32_e32 v16, 16, v48
	v_and_b32_e32 v17, 0xffff0000, v48
	v_lshlrev_b32_e32 v18, 16, v49
	v_and_b32_e32 v19, 0xffff0000, v49
	v_pk_fma_f32 v[16:17], v[24:25], v[32:33], v[16:17] op_sel_hi:[1,0,1]
	v_pk_fma_f32 v[18:19], v[26:27], v[32:33], v[18:19] op_sel_hi:[1,0,1]
	v_cvt_pk_bf16_f32 v16, v16, v17
	v_cvt_pk_bf16_f32 v17, v18, v19
	global_store_dwordx2 v[140:141], v[16:17], off offset:32
	s_waitcnt vmcnt(7)
	v_lshlrev_b32_e32 v16, 16, v42
	v_and_b32_e32 v17, 0xffff0000, v42
	v_lshlrev_b32_e32 v18, 16, v43
	v_and_b32_e32 v19, 0xffff0000, v43
	v_pk_fma_f32 v[16:17], v[28:29], v[32:33], v[16:17] op_sel_hi:[1,0,1]
	v_pk_fma_f32 v[18:19], v[30:31], v[32:33], v[18:19] op_sel_hi:[1,0,1]
	v_cvt_pk_bf16_f32 v16, v16, v17
	v_cvt_pk_bf16_f32 v17, v18, v19
	global_store_dwordx2 v[140:141], v[16:17], off offset:48
	s_waitcnt vmcnt(7)
	v_lshlrev_b32_e32 v16, 16, v40
	v_and_b32_e32 v17, 0xffff0000, v40
	v_pk_fma_f32 v[0:1], v[0:1], v[32:33], v[16:17] op_sel_hi:[1,0,1]
	v_lshlrev_b32_e32 v16, 16, v41
	v_and_b32_e32 v17, 0xffff0000, v41
	v_pk_fma_f32 v[2:3], v[2:3], v[32:33], v[16:17] op_sel_hi:[1,0,1]
	v_cvt_pk_bf16_f32 v0, v0, v1
	v_cvt_pk_bf16_f32 v1, v2, v3
	global_store_dwordx2 v[140:141], v[0:1], off offset:64
	s_waitcnt vmcnt(7)
	v_lshlrev_b32_e32 v0, 16, v38
	v_and_b32_e32 v1, 0xffff0000, v38
	v_lshlrev_b32_e32 v2, 16, v39
	v_and_b32_e32 v3, 0xffff0000, v39
	v_pk_fma_f32 v[0:1], v[4:5], v[32:33], v[0:1] op_sel_hi:[1,0,1]
	v_pk_fma_f32 v[2:3], v[6:7], v[32:33], v[2:3] op_sel_hi:[1,0,1]
	v_cvt_pk_bf16_f32 v0, v0, v1
	v_cvt_pk_bf16_f32 v1, v2, v3
	global_store_dwordx2 v[140:141], v[0:1], off offset:80
	s_waitcnt vmcnt(7)
	v_lshlrev_b32_e32 v0, 16, v36
	v_and_b32_e32 v1, 0xffff0000, v36
	v_lshlrev_b32_e32 v2, 16, v37
	v_and_b32_e32 v3, 0xffff0000, v37
	v_pk_fma_f32 v[0:1], v[8:9], v[32:33], v[0:1] op_sel_hi:[1,0,1]
	v_pk_fma_f32 v[2:3], v[10:11], v[32:33], v[2:3] op_sel_hi:[1,0,1]
	v_cvt_pk_bf16_f32 v0, v0, v1
	v_cvt_pk_bf16_f32 v1, v2, v3
	global_store_dwordx2 v[140:141], v[0:1], off offset:96
	s_waitcnt vmcnt(7)
	v_lshlrev_b32_e32 v0, 16, v34
	v_and_b32_e32 v1, 0xffff0000, v34
	v_lshlrev_b32_e32 v2, 16, v35
	v_and_b32_e32 v3, 0xffff0000, v35
	v_pk_fma_f32 v[0:1], v[12:13], v[32:33], v[0:1] op_sel_hi:[1,0,1]
	v_pk_fma_f32 v[2:3], v[14:15], v[32:33], v[2:3] op_sel_hi:[1,0,1]
	v_cvt_pk_bf16_f32 v0, v0, v1
	v_cvt_pk_bf16_f32 v1, v2, v3
	global_store_dwordx2 v[140:141], v[0:1], off offset:112
	s_cbranch_scc1 .LBB0_274

; DI unsigned cvtpk(float lo, float hi) { return pg8::cvt_pk_bf16(lo, hi); }
; DI float bflo(unsigned w) { return __uint_as_float(w << 16); }
; DI float bfhi(unsigned w) { return __uint_as_float(w & 0xffff0000u); }
; template <bool FIRST> DI void attn_flush(const AttnSt& st, const float (&sc)[NRT], bf16_t* const (&orow)[NRT]) {
;     ...
;         for (int dt = 0; dt < 2; ++dt)
; #pragma unroll
;             for (int q4 = 0; q4 < 4; ++q4) { u32x2* p = (u32x2*)(orow[rt] + dt * 32 + 8 * q4); float v0 = st.o[dt][rt][4 * q4] * sc[rt], v1 = st.o[dt][rt][4 * q4 + 1] * sc[rt], v2 = st.o[dt][rt][4 * q4 + 2] * sc[rt], v3 = st.o[dt][rt][4 * q4 + 3] * sc[rt];
;                 if (!FIRST) { v0 += bflo(old[dt][q4].x); v1 += bfhi(old[dt][q4].x); v2 += bflo(old[dt][q4].y); v3 += bfhi(old[dt][q4].y); }
;                 u32x2 w; w.x = cvtpk(v0, v1); w.y = cvtpk(v2, v3); *p = w; } }
; DI void nsa_wg_unit(const Args& a, int l, int b, int g, int tb, unsigned char* lds, int tid_in, bool stage) {
;     ...
;     { const int tok = lane / LPT, qtr = lane % LPT; float mv[CPL];
; #pragma unroll
;       for (int c = 0; c < CPL; ++c) { const int j = qtr * CPL + c; float v = IA[tok * 65 + j] + IB[tok * 65 + j]; const bool forced = (j == 0) | (j == jt) | (j == jt - 1); v = forced ? 1e6f : (j > jt ? -1e30f : v); mv[c] = v; }
.LBB0_138:
	v_add_f32_e32 v34, 1.0, v78
	v_div_scale_f32 v35, s[6:7], v34, v34, 1.0
	v_rcp_f32_e32 v36, v35
	s_lshl_b64 s[0:1], s[30:31], 22
	v_readlane_b32 s6, v254, 36
	s_add_u32 s42, s6, s0
	v_fma_f32 v37, -v35, v36, 1.0
	v_fmac_f32_e32 v36, v37, v36
	v_div_scale_f32 v37, vcc, 1.0, v34, 1.0
	v_mul_f32_e32 v38, v37, v36
	v_fma_f32 v39, -v35, v38, v37
	v_fmac_f32_e32 v38, v39, v36
	v_readlane_b32 s0, v254, 37
	v_fma_f32 v35, -v35, v38, v37
	v_lshlrev_b64 v[32:33], 10, v[136:137]
	s_addc_u32 s43, s0, s1
	v_div_fmas_f32 v35, v35, v36, v38
	v_lshl_add_u64 v[32:33], s[42:43], 0, v[32:33]
	v_div_fixup_f32 v34, v35, v34, 1.0
	v_lshlrev_b32_e32 v160, 1, v62
	v_lshl_add_u64 v[32:33], v[32:33], 0, v[160:161]
	v_lshlrev_b32_e32 v160, 1, v156
	v_pk_mul_f32 v[16:17], v[34:35], v[16:17] op_sel_hi:[0,1]
	v_pk_mul_f32 v[18:19], v[34:35], v[18:19] op_sel_hi:[0,1]
	v_pk_mul_f32 v[0:1], v[34:35], v[0:1] op_sel_hi:[0,1]
	v_pk_mul_f32 v[2:3], v[34:35], v[2:3] op_sel_hi:[0,1]
	v_lshl_add_u64 v[140:141], v[32:33], 0, v[160:161]
	v_cvt_pk_bf16_f32 v16, v16, v17
	v_cvt_pk_bf16_f32 v17, v18, v19
	v_cvt_pk_bf16_f32 v0, v0, v1
	v_cvt_pk_bf16_f32 v1, v2, v3
	v_mov_b64_e32 v[236:237], v[16:17]
	v_pk_mul_f32 v[16:17], v[34:35], v[20:21] op_sel_hi:[0,1]
	v_pk_mul_f32 v[18:19], v[34:35], v[22:23] op_sel_hi:[0,1]
	v_mov_b64_e32 v[244:245], v[0:1]
	v_pk_mul_f32 v[0:1], v[34:35], v[4:5] op_sel_hi:[0,1]
	v_pk_mul_f32 v[2:3], v[34:35], v[6:7] op_sel_hi:[0,1]
	v_cvt_pk_bf16_f32 v16, v16, v17
	v_cvt_pk_bf16_f32 v17, v18, v19
	v_cvt_pk_bf16_f32 v0, v0, v1
	v_cvt_pk_bf16_f32 v1, v2, v3
	v_mov_b64_e32 v[238:239], v[16:17]
	v_pk_mul_f32 v[16:17], v[34:35], v[24:25] op_sel_hi:[0,1]
	v_pk_mul_f32 v[18:19], v[34:35], v[26:27] op_sel_hi:[0,1]
	v_mov_b64_e32 v[246:247], v[0:1]
	v_pk_mul_f32 v[0:1], v[34:35], v[8:9] op_sel_hi:[0,1]
	v_pk_mul_f32 v[2:3], v[34:35], v[10:11] op_sel_hi:[0,1]
	v_cvt_pk_bf16_f32 v16, v16, v17
	v_cvt_pk_bf16_f32 v17, v18, v19
	v_cvt_pk_bf16_f32 v0, v0, v1
	v_cvt_pk_bf16_f32 v1, v2, v3
	v_mov_b64_e32 v[240:241], v[16:17]
	v_pk_mul_f32 v[16:17], v[34:35], v[28:29] op_sel_hi:[0,1]
	v_pk_mul_f32 v[18:19], v[34:35], v[30:31] op_sel_hi:[0,1]
	v_mov_b64_e32 v[248:249], v[0:1]
	v_pk_mul_f32 v[0:1], v[34:35], v[12:13] op_sel_hi:[0,1]
	v_pk_mul_f32 v[2:3], v[34:35], v[14:15] op_sel_hi:[0,1]
	v_cvt_pk_bf16_f32 v16, v16, v17
	v_cvt_pk_bf16_f32 v17, v18, v19
	v_cvt_pk_bf16_f32 v0, v0, v1
	v_cvt_pk_bf16_f32 v1, v2, v3
	v_and_b32_e32 v32, 7, v71
	v_mov_b64_e32 v[242:243], v[16:17]
	v_mov_b64_e32 v[250:251], v[0:1]
	v_lshlrev_b32_e32 v0, 3, v32
	s_waitcnt lgkmcnt(0)
	s_add_i32 s10, s33, -1
	v_cmp_ne_u32_e32 vcc, 0, v32
	v_cmp_ne_u32_e64 s[6:7], s33, v0
	v_lshrrev_b32_e32 v1, 3, v73
	s_and_b64 s[0:1], vcc, s[6:7]
	v_cmp_ne_u32_e32 vcc, s10, v0
	v_mul_u32_u24_e32 v3, 0x41, v1
	s_and_b64 s[6:7], vcc, s[0:1]
	v_mov_b32_e32 v2, 0x49742400
	v_mov_b32_e32 v4, 0x49742400
	s_and_saveexec_b64 s[0:1], s[6:7]
	s_cbranch_execz .LBB0_140
	v_add_u32_e32 v4, v3, v0
	v_lshl_add_u32 v4, v4, 2, s9
	ds_read_b32 v5, v4
	ds_read_b32 v4, v4 offset:2080
	v_cmp_ge_u32_e32 vcc, s33, v0
	s_waitcnt lgkmcnt(0)
	v_add_f32_e32 v4, v5, v4
	v_cndmask_b32_e32 v4, v219, v4, vcc

; DI unsigned cvtpk(float lo, float hi) { return pg8::cvt_pk_bf16(lo, hi); }
; DI float bflo(unsigned w) { return __uint_as_float(w << 16); }
; DI float bfhi(unsigned w) { return __uint_as_float(w & 0xffff0000u); }
; template <bool FIRST> DI void attn_flush(const AttnSt& st, const float (&sc)[NRT], bf16_t* const (&orow)[NRT]) {
;     ...
;     for (int rt = 0; rt < NRT; ++rt) { u32x2 old[2][4];
;         if (!FIRST) {
; #pragma unroll
;             for (int dt = 0; dt < 2; ++dt)
; #pragma unroll
;                 for (int q4 = 0; q4 < 4; ++q4) old[dt][q4] = *(const u32x2*)(orow[rt] + dt * 32 + 8 * q4); }
; #pragma unroll
;         for (int dt = 0; dt < 2; ++dt)
; #pragma unroll
;             for (int q4 = 0; q4 < 4; ++q4) { u32x2* p = (u32x2*)(orow[rt] + dt * 32 + 8 * q4); float v0 = st.o[dt][rt][4 * q4] * sc[rt], v1 = st.o[dt][rt][4 * q4 + 1] * sc[rt], v2 = st.o[dt][rt][4 * q4 + 2] * sc[rt], v3 = st.o[dt][rt][4 * q4 + 3] * sc[rt];
;                 if (!FIRST) { v0 += bflo(old[dt][q4].x); v1 += bfhi(old[dt][q4].x); v2 += bflo(old[dt][q4].y); v3 += bfhi(old[dt][q4].y); }
;                 u32x2 w; w.x = cvtpk(v0, v1); w.y = cvtpk(v2, v3); *p = w; } }
; DI void nsa_wg_unit(const Args& a, int l, int b, int g, int tb, unsigned char* lds, int tid_in, bool stage) {
;     ...
;     { float sc[NRT]; const float lt = st.l[0] + __shfl_xor(st.l[0], 32); sc[0] = lt > 0.f ? gt[0][1] / lt : 0.f; attn_flush<false>(st, sc, orow); }
;     attn_reset(st);
;     { const unsigned koff = (unsigned)(srow * ZP + sch * 8) * 2u, voff = (unsigned)(srow * SEQ + sch * 8) * 2u; const char* kgb = (const char*)(zb + C_KV + 4 * 128 + g * 64); const char* vgb = (const char*)VWT;
;       int j = tb - 8 < 0 ? 0 : tb - 8, bi = 0; u32x4 kreg, vreg;
;       { kreg = *(const u32x4*)(kgb + (size_t)(64 * j) * ZP * 2 + koff); vreg = *(const u32x4*)(vgb + (size_t)(64 * j) * 2 + voff);
;         *(u32x4*)(lds + AL_KR + srow * KR_PB + sch * 16) = kreg; u32x2* d = (u32x2*)(lds + AL_VR + srow * VR_PB + sch * 16); u32x2 lo2, hi2; lo2.x = vreg.x; lo2.y = vreg.y; hi2.x = vreg.z; hi2.y = vreg.w; d[0] = lo2; d[1] = hi2; }
;       __syncthreads();
.LBB0_183:
	v_mov_b64_e32 v[32:33], v[236:237]
	v_mov_b64_e32 v[34:35], v[238:239]
	v_mov_b64_e32 v[36:37], v[240:241]
	v_mov_b64_e32 v[38:39], v[242:243]
	v_mov_b64_e32 v[40:41], v[244:245]
	v_mov_b64_e32 v[42:43], v[246:247]
	v_mov_b64_e32 v[44:45], v[248:249]
	v_mov_b64_e32 v[46:47], v[250:251]
	v_add_f32_e32 v48, 1.0, v159
	v_div_scale_f32 v50, s[8:9], v48, v48, 1.0
	v_rcp_f32_e32 v52, v50
	v_div_scale_f32 v51, vcc, 1.0, v48, 1.0
	ds_bpermute_b32 v49, v148, v171
	v_fma_f32 v53, -v50, v52, 1.0
	v_fmac_f32_e32 v52, v53, v52
	v_mul_f32_e32 v53, v51, v52
	s_add_u32 s0, s46, s10
	v_fma_f32 v54, -v50, v53, v51
	s_addc_u32 s1, s47, 0
	v_fmac_f32_e32 v53, v54, v52
	s_lshl_b64 s[0:1], s[0:1], 19
	v_readlane_b32 s7, v254, 32
	v_fma_f32 v50, -v50, v53, v51
	s_add_u32 s0, s7, s0
	v_readlane_b32 s7, v254, 34
	v_div_fmas_f32 v50, v50, v52, v53
	s_addc_u32 s7, s7, s1
	s_waitcnt lgkmcnt(0)
	v_add_f32_e32 v49, v171, v49
	v_div_fixup_f32 v48, v50, v48, 1.0
	s_add_u32 s2, s0, 0x800000
	v_div_scale_f32 v50, s[0:1], v49, v49, v48
	v_rcp_f32_e32 v51, v50
	v_div_scale_f32 v52, vcc, v48, v49, v48
	s_addc_u32 s35, s7, 0
	v_fma_f32 v53, -v50, v51, 1.0
	v_fmac_f32_e32 v51, v53, v51
	v_mul_f32_e32 v53, v52, v51
	v_fma_f32 v54, -v50, v53, v52
	v_fmac_f32_e32 v53, v54, v51
	v_fma_f32 v50, -v50, v53, v52
	v_div_fmas_f32 v50, v50, v51, v53
	v_div_fixup_f32 v48, v50, v49, v48
	v_cmp_lt_f32_e32 vcc, 0, v49
	s_lshl_b32 s0, s6, 1
	s_add_u32 s0, s36, s0
	v_cndmask_b32_e32 v48, 0, v48, vcc
	s_addc_u32 s1, s37, 0
	s_add_u32 s45, s0, 0x1400
	s_addc_u32 s46, s1, 0
	s_max_i32 s0, s33, 8
	s_add_i32 s1, s0, -8
	s_lshl_b32 s6, s1, 6
	s_mul_i32 s7, s1, 0x88c00
	s_mul_hi_u32 s8, s6, 0x2230
	s_add_u32 s6, s45, s7
	s_addc_u32 s7, s46, s8
	v_add3_u32 v146, s26, v137, v138
	v_add3_u32 v138, s28, v168, v138
	s_waitcnt vmcnt(7)
	v_lshlrev_b32_e32 v50, 16, v32
	v_and_b32_e32 v51, 0xffff0000, v32
	v_lshlrev_b32_e32 v32, 16, v33
	v_and_b32_e32 v33, 0xffff0000, v33
	s_waitcnt vmcnt(6)
	v_lshlrev_b32_e32 v52, 16, v34
	v_and_b32_e32 v53, 0xffff0000, v34
	v_lshlrev_b32_e32 v34, 16, v35
	v_and_b32_e32 v35, 0xffff0000, v35
	s_waitcnt vmcnt(5)
	v_lshlrev_b32_e32 v54, 16, v36
	v_and_b32_e32 v55, 0xffff0000, v36
	v_lshlrev_b32_e32 v36, 16, v37
	v_and_b32_e32 v37, 0xffff0000, v37
	s_waitcnt vmcnt(4)
	v_lshlrev_b32_e32 v56, 16, v38
	v_and_b32_e32 v57, 0xffff0000, v38
	v_lshlrev_b32_e32 v38, 16, v39
	v_and_b32_e32 v39, 0xffff0000, v39
	v_pk_fma_f32 v[16:17], v[16:17], v[48:49], v[50:51] op_sel_hi:[1,0,1]
	v_pk_fma_f32 v[18:19], v[18:19], v[48:49], v[32:33] op_sel_hi:[1,0,1]
	v_pk_fma_f32 v[20:21], v[20:21], v[48:49], v[52:53] op_sel_hi:[1,0,1]
	v_pk_fma_f32 v[22:23], v[22:23], v[48:49], v[34:35] op_sel_hi:[1,0,1]
	v_pk_fma_f32 v[24:25], v[24:25], v[48:49], v[54:55] op_sel_hi:[1,0,1]
	v_pk_fma_f32 v[26:27], v[26:27], v[48:49], v[36:37] op_sel_hi:[1,0,1]
	v_pk_fma_f32 v[28:29], v[28:29], v[48:49], v[56:57] op_sel_hi:[1,0,1]
	v_pk_fma_f32 v[30:31], v[30:31], v[48:49], v[38:39] op_sel_hi:[1,0,1]
	v_cvt_pk_bf16_f32 v16, v16, v17
	v_cvt_pk_bf16_f32 v17, v18, v19
	v_cvt_pk_bf16_f32 v18, v20, v21
	v_cvt_pk_bf16_f32 v19, v22, v23
	v_cvt_pk_bf16_f32 v20, v24, v25
	v_cvt_pk_bf16_f32 v21, v26, v27
	v_cvt_pk_bf16_f32 v22, v28, v29
	v_cvt_pk_bf16_f32 v23, v30, v31
	v_mov_b64_e32 v[236:237], v[16:17]
	v_mov_b64_e32 v[238:239], v[18:19]
	v_mov_b64_e32 v[240:241], v[20:21]
	v_mov_b64_e32 v[242:243], v[22:23]
	s_waitcnt vmcnt(7)
	v_lshlrev_b32_e32 v16, 16, v40
	v_and_b32_e32 v17, 0xffff0000, v40
	v_pk_fma_f32 v[0:1], v[0:1], v[48:49], v[16:17] op_sel_hi:[1,0,1]
	v_lshlrev_b32_e32 v16, 16, v41
	v_and_b32_e32 v17, 0xffff0000, v41
	v_pk_fma_f32 v[2:3], v[2:3], v[48:49], v[16:17] op_sel_hi:[1,0,1]
	v_cvt_pk_bf16_f32 v0, v0, v1
	v_cvt_pk_bf16_f32 v1, v2, v3
	v_mov_b64_e32 v[244:245], v[0:1]
	s_waitcnt vmcnt(7)
	v_lshlrev_b32_e32 v0, 16, v42
	v_and_b32_e32 v1, 0xffff0000, v42
	v_lshlrev_b32_e32 v2, 16, v43
	v_and_b32_e32 v3, 0xffff0000, v43
	v_pk_fma_f32 v[0:1], v[4:5], v[48:49], v[0:1] op_sel_hi:[1,0,1]
	v_pk_fma_f32 v[2:3], v[6:7], v[48:49], v[2:3] op_sel_hi:[1,0,1]
	v_cvt_pk_bf16_f32 v0, v0, v1
	v_cvt_pk_bf16_f32 v1, v2, v3
	v_mov_b64_e32 v[246:247], v[0:1]
	s_waitcnt vmcnt(7)
	v_lshlrev_b32_e32 v0, 16, v44
	v_and_b32_e32 v1, 0xffff0000, v44
	v_lshlrev_b32_e32 v2, 16, v45
	v_and_b32_e32 v3, 0xffff0000, v45
	v_pk_fma_f32 v[0:1], v[8:9], v[48:49], v[0:1] op_sel_hi:[1,0,1]
	v_pk_fma_f32 v[2:3], v[10:11], v[48:49], v[2:3] op_sel_hi:[1,0,1]
	v_cvt_pk_bf16_f32 v0, v0, v1
	v_cvt_pk_bf16_f32 v1, v2, v3
	v_mov_b64_e32 v[248:249], v[0:1]
	s_waitcnt vmcnt(7)
	v_lshlrev_b32_e32 v0, 16, v46
	v_and_b32_e32 v1, 0xffff0000, v46
	v_lshlrev_b32_e32 v2, 16, v47
	v_and_b32_e32 v3, 0xffff0000, v47
	v_pk_fma_f32 v[0:1], v[12:13], v[48:49], v[0:1] op_sel_hi:[1,0,1]
	v_pk_fma_f32 v[2:3], v[14:15], v[48:49], v[2:3] op_sel_hi:[1,0,1]
	v_cvt_pk_bf16_f32 v0, v0, v1
	v_cvt_pk_bf16_f32 v1, v2, v3
	v_mov_b64_e32 v[250:251], v[0:1]
	v_lshl_add_u64 v[0:1], s[6:7], 0, v[142:143]
	s_lshl_b32 s6, s1, 7
	s_add_u32 s6, s2, s6
	s_addc_u32 s7, s35, 0
	v_lshl_add_u64 v[2:3], s[6:7], 0, v[160:161]
	global_load_dwordx4 v[96:99], v[0:1], off
	global_load_dwordx4 v[100:103], v[2:3], off
	v_mov_b32_e32 v15, 0
	v_mov_b32_e32 v14, v15
	v_mov_b32_e32 v13, v15
	v_mov_b32_e32 v12, v15
	v_mov_b32_e32 v11, v15
	v_mov_b32_e32 v10, v15
	v_mov_b32_e32 v9, v15
	v_mov_b32_e32 v8, v15
	v_mov_b32_e32 v7, v15
	v_mov_b32_e32 v6, v15
	v_mov_b32_e32 v5, v15
	v_mov_b32_e32 v4, v15
	v_mov_b32_e32 v3, v15
	v_mov_b32_e32 v2, v15
	v_mov_b32_e32 v1, v15
	v_mov_b32_e32 v0, v15
	v_mov_b32_e32 v31, v15
	v_mov_b32_e32 v30, v15
	s_cmp_gt_i32 s1, s33
	v_mov_b32_e32 v29, v15
	v_mov_b32_e32 v28, v15
	v_mov_b32_e32 v27, v15
	v_mov_b32_e32 v26, v15
	v_mov_b32_e32 v25, v15
	v_mov_b32_e32 v24, v15
	v_mov_b32_e32 v23, v15
	v_mov_b32_e32 v22, v15
	v_mov_b32_e32 v21, v15
	v_mov_b32_e32 v20, v15
	v_mov_b32_e32 v19, v15
	v_mov_b32_e32 v18, v15
	v_mov_b32_e32 v17, v15
	v_mov_b32_e32 v16, v15
	v_mov_b32_e32 v137, v15
	s_waitcnt vmcnt(1)
	ds_write_b128 v146, v[96:99]
	s_waitcnt vmcnt(0)
	ds_write2_b64 v138, v[100:101], v[102:103] offset1:1
	s_waitcnt lgkmcnt(0)
	s_barrier
; DI void nsa_wg_unit(const Args& a, int l, int b, int g, int tb, unsigned char* lds, int tid_in, bool stage) {
;     ...
;       for (; j <= tb; ++j) { const bool hn = j + 1 <= tb;
;           if (hn) { kreg = *(const u32x4*)(kgb + (size_t)(64 * (j + 1)) * ZP * 2 + koff); vreg = *(const u32x4*)(vgb + (size_t)(64 * (j + 1)) * 2 + voff); }
;           if (64 * j + 63 >= t0 - 511 && 64 * j <= t0 + NTOK - 1)
;               attn_block64(st, qf, kfl + bi * KR_SZ, vfl + bi * VR_SZ, KR_PB, VR_PB, cref[2], true, (64 * j + 63 > t0) || (64 * j <= t0 + NTOK - 1 - 512), MaskWindow{tk[0]}, 64 * j, h);
	s_cbranch_scc1 .LBB0_196
	v_readlane_b32 s8, v254, 56
	s_lshl_b32 s1, s0, 6
	v_readlane_b32 s9, v254, 57
	s_add_i32 s12, s93, 0xfffffe01
	s_add_i32 s13, s93, 0xfffffe07
	s_add_i32 s14, s1, 0xfffffe00
	s_add_i32 s15, s0, -9
	s_lshl_b64 s[8:9], s[8:9], 20
	s_lshl_b32 s1, s10, 19
	s_lshl_b32 s10, s0, 7
	v_readlane_b32 s11, v254, 40
	s_add_u32 s10, s11, s10
	v_readlane_b32 s11, v254, 41
	s_addc_u32 s11, s11, 0
	s_add_u32 s1, s10, s1
	s_addc_u32 s10, s11, 0
	s_add_u32 s8, s1, s8
	s_addc_u32 s9, s10, s9
	v_lshl_add_u64 v[144:145], s[8:9], 0, v[160:161]
	v_readlane_b32 s1, v254, 42
	v_readlane_b32 s8, v254, 55
	s_add_u32 s1, s1, s8
	v_readlane_b32 s8, v254, 43
	s_mul_i32 s0, s0, 0x88c00
	s_addc_u32 s8, s8, 0
	s_add_u32 s0, s1, s0
	v_mul_f32_e32 v0, v157, v158
	s_addc_u32 s1, s8, 0
	v_readlane_b32 s8, v254, 52
	v_cmp_lt_f32_e32 vcc, s25, v0
	s_add_u32 s0, s0, s8
	v_readlane_b32 s8, v254, 53
	v_mov_b32_e32 v137, 0
	v_cndmask_b32_e32 v32, 0, v0, vcc
	s_addc_u32 s1, s1, s8
	v_add_u32_e32 v147, 0xfffffe00, v136
	v_cmp_neq_f32_e64 s[6:7], 0, v32
	v_mov_b32_e32 v33, v32
	v_mov_b32_e32 v34, v32
	v_mov_b32_e32 v35, v32
	v_mov_b32_e32 v36, v32
	v_mov_b32_e32 v37, v32
	v_mov_b32_e32 v38, v32
	v_mov_b32_e32 v39, v32
	v_mov_b32_e32 v40, v32
	v_mov_b32_e32 v41, v32
	v_mov_b32_e32 v42, v32
	v_mov_b32_e32 v43, v32
	v_mov_b32_e32 v44, v32
	v_lshl_add_u64 v[142:143], s[0:1], 0, v[142:143]
	s_mov_b32 s16, 0
	v_mov_b32_e32 v0, 0
	v_mov_b32_e32 v1, v137
	v_mov_b32_e32 v2, v137
	v_mov_b32_e32 v3, v137
	v_mov_b32_e32 v4, v137
	v_mov_b32_e32 v5, v137
	v_mov_b32_e32 v6, v137
	v_mov_b32_e32 v7, v137
	v_mov_b32_e32 v8, v137
	v_mov_b32_e32 v9, v137
	v_mov_b32_e32 v10, v137
	v_mov_b32_e32 v11, v137
	v_mov_b32_e32 v12, v137
	v_mov_b32_e32 v13, v137
	v_mov_b32_e32 v14, v137
	v_mov_b32_e32 v15, v137
	v_mov_b32_e32 v16, 0
	v_mov_b32_e32 v17, v137
	v_mov_b32_e32 v18, v137
	v_mov_b32_e32 v19, v137
	v_mov_b32_e32 v20, v137
	v_mov_b32_e32 v21, v137
	v_mov_b32_e32 v22, v137
	v_mov_b32_e32 v23, v137
	v_mov_b32_e32 v24, v137
	v_mov_b32_e32 v25, v137
	v_mov_b32_e32 v26, v137
	v_mov_b32_e32 v27, v137
	v_mov_b32_e32 v28, v137
	v_mov_b32_e32 v29, v137
	v_mov_b32_e32 v30, v137
	v_mov_b32_e32 v31, v137
	v_mov_b32_e32 v45, v32
	v_mov_b32_e32 v46, v32
	v_mov_b32_e32 v47, v32
	s_branch .LBB0_186

; template <bool FIRST> DI void attn_flush(const AttnSt& st, const float (&sc)[NRT], bf16_t* const (&orow)[NRT]) {
;     ...
;     for (int rt = 0; rt < NRT; ++rt) { u32x2 old[2][4];
;         if (!FIRST) {
; #pragma unroll
;             for (int dt = 0; dt < 2; ++dt)
; #pragma unroll
;                 for (int q4 = 0; q4 < 4; ++q4) old[dt][q4] = *(const u32x2*)(orow[rt] + dt * 32 + 8 * q4); }
; #pragma unroll
;         for (int dt = 0; dt < 2; ++dt)
; #pragma unroll
;             for (int q4 = 0; q4 < 4; ++q4) { u32x2* p = (u32x2*)(orow[rt] + dt * 32 + 8 * q4); float v0 = st.o[dt][rt][4 * q4] * sc[rt], v1 = st.o[dt][rt][4 * q4 + 1] * sc[rt], v2 = st.o[dt][rt][4 * q4 + 2] * sc[rt], v3 = st.o[dt][rt][4 * q4 + 3] * sc[rt];
;                 if (!FIRST) { v0 += bflo(old[dt][q4].x); v1 += bfhi(old[dt][q4].x); v2 += bflo(old[dt][q4].y); v3 += bfhi(old[dt][q4].y); }
;                 u32x2 w; w.x = cvtpk(v0, v1); w.y = cvtpk(v2, v3); *p = w; } }
; DI void nsa_wg_unit(const Args& a, int l, int b, int g, int tb, unsigned char* lds, int tid_in, bool stage) {
;     ...
;     const bf16_t* KC = (const bf16_t*)(a.ws + WS_KC) + ((size_t)b * 2 + g) * 256 * 64; const bf16_t* VCT = (const bf16_t*)(a.ws + WS_VCT) + ((size_t)b * 2 + g) * 64 * 256;
;     const bf16_t* VST = (const bf16_t*)(a.ws + WS_VT) + (((size_t)0 * NB + b) * 2 + g) * 64 * SEQ; const bf16_t* VWT = (const bf16_t*)(a.ws + WS_VT) + (((size_t)1 * NB + b) * 2 + g) * 64 * SEQ;
;     bf16_t* OB = (bf16_t*)(a.ws + WS_OUTS) + (size_t)MROWS * 512;
;     const int rl = lane & 31, h = lane >> 5, head = rl & 3, t0 = tb * 64 + wave * 8, jt = tb;
;     int tk[NRT]; tk[0] = t0 + (rl >> 2);
;     const bf16_t* zb = Z1 + (size_t)b * SEQ * ZP;
;     LP L = (LP)lds;
;     __syncthreads();
;     if (stage) {
;     for (int i = tid; i < 2048; i += 512) { const int row = i >> 3, ch = i & 7; *(u32x4*)(lds + AL_KC + row * KC_PB + ch * 16) = *(const u32x4*)(KC + row * 64 + ch * 8); }
;     for (int i = tid; i < 2048; i += 512) { const int row = i >> 5, ch = i & 31; const u32x4 v = *(const u32x4*)(VCT + row * 256 + ch * 8); u32x2* d = (u32x2*)(lds + AL_VC + row * VC_PB + ch * 16); u32x2 lo, hi; lo.x = v.x; lo.y = v.y; hi.x = v.z; hi.y = v.w; d[0] = lo; d[1] = hi; }
;     }
;     bf16x8 qf[NRT][4]; float gt[NRT][3]; bf16_t* orow[NRT];
;     { const bf16_t* zr = zb + (size_t)tk[0] * ZP;
; #pragma unroll
.LBB0_196:
	v_mov_b64_e32 v[32:33], v[236:237]
	v_mov_b64_e32 v[34:35], v[238:239]
	v_mov_b64_e32 v[36:37], v[240:241]
	v_mov_b64_e32 v[38:39], v[242:243]
	v_mov_b64_e32 v[40:41], v[244:245]
	v_lshlrev_b32_e32 v42, 16, v139
	v_mul_f32_e32 v42, 0xbfb8aa3b, v42
	v_exp_f32_e32 v136, v42
	v_mov_b64_e32 v[42:43], v[246:247]
	v_mov_b64_e32 v[46:47], v[248:249]
	v_mov_b64_e32 v[48:49], v[250:251]
	ds_bpermute_b32 v165, v148, v137
	v_mov_b32_e32 v74, v225
	s_xor_b32 s93, s33, 63
	s_lshl_b32 s68, s93, 6
	v_mov_b32_e32 v61, v161
	s_waitcnt lgkmcnt(0)
	v_pk_add_f32 v[44:45], v[136:137], v[164:165]
	s_waitcnt vmcnt(5)
	v_and_b32_e32 v55, 0xffff0000, v36
	v_div_scale_f32 v50, s[0:1], v44, v44, 1.0
	v_rcp_f32_e32 v51, v50
	v_div_scale_f32 v52, vcc, 1.0, v44, 1.0
	s_waitcnt vmcnt(3)
	v_lshlrev_b32_e32 v58, 16, v40
	v_fma_f32 v53, -v50, v51, 1.0
	v_fmac_f32_e32 v51, v53, v51
	v_mul_f32_e32 v53, v52, v51
	v_fma_f32 v54, -v50, v53, v52
	v_fmac_f32_e32 v53, v54, v51
	v_fma_f32 v50, -v50, v53, v52
	v_div_fmas_f32 v50, v50, v51, v53
	v_div_fixup_f32 v44, v50, v44, 1.0
	v_div_scale_f32 v50, s[0:1], v45, v45, v44
	v_rcp_f32_e32 v51, v50
	v_div_scale_f32 v52, vcc, v44, v45, v44
	v_and_b32_e32 v59, 0xffff0000, v40
	v_fma_f32 v53, -v50, v51, 1.0
	v_fmac_f32_e32 v51, v53, v51
	v_mul_f32_e32 v53, v52, v51
	v_fma_f32 v54, -v50, v53, v52
	v_fmac_f32_e32 v53, v54, v51
	v_fma_f32 v50, -v50, v53, v52
	v_div_fmas_f32 v50, v50, v51, v53
	v_div_fixup_f32 v44, v50, v45, v44
	v_cmp_lt_f32_e32 vcc, 0, v45
	v_lshlrev_b32_e32 v50, 16, v32
	v_and_b32_e32 v51, 0xffff0000, v32
	v_cndmask_b32_e32 v44, 0, v44, vcc
	v_lshlrev_b32_e32 v32, 16, v33
	v_and_b32_e32 v33, 0xffff0000, v33
	v_lshlrev_b32_e32 v40, 16, v41
	v_and_b32_e32 v41, 0xffff0000, v41
	v_lshlrev_b32_e32 v52, 16, v34
	v_and_b32_e32 v53, 0xffff0000, v34
	v_lshlrev_b32_e32 v34, 16, v35
	v_and_b32_e32 v35, 0xffff0000, v35
	v_lshlrev_b32_e32 v54, 16, v36
	v_lshlrev_b32_e32 v36, 16, v37
	v_and_b32_e32 v37, 0xffff0000, v37
	v_lshlrev_b32_e32 v56, 16, v38
	v_and_b32_e32 v57, 0xffff0000, v38
	v_lshlrev_b32_e32 v38, 16, v39
	v_and_b32_e32 v39, 0xffff0000, v39
	v_pk_fma_f32 v[16:17], v[16:17], v[44:45], v[50:51] op_sel_hi:[1,0,1]
	v_pk_fma_f32 v[18:19], v[18:19], v[44:45], v[32:33] op_sel_hi:[1,0,1]
	v_pk_fma_f32 v[0:1], v[0:1], v[44:45], v[58:59] op_sel_hi:[1,0,1]
	v_pk_fma_f32 v[2:3], v[2:3], v[44:45], v[40:41] op_sel_hi:[1,0,1]
	v_pk_fma_f32 v[20:21], v[20:21], v[44:45], v[52:53] op_sel_hi:[1,0,1]
	v_pk_fma_f32 v[22:23], v[22:23], v[44:45], v[34:35] op_sel_hi:[1,0,1]
	v_pk_fma_f32 v[24:25], v[24:25], v[44:45], v[54:55] op_sel_hi:[1,0,1]
	v_pk_fma_f32 v[26:27], v[26:27], v[44:45], v[36:37] op_sel_hi:[1,0,1]
	v_pk_fma_f32 v[28:29], v[28:29], v[44:45], v[56:57] op_sel_hi:[1,0,1]
	v_pk_fma_f32 v[30:31], v[30:31], v[44:45], v[38:39] op_sel_hi:[1,0,1]
	v_cvt_pk_bf16_f32 v16, v16, v17
	v_cvt_pk_bf16_f32 v17, v18, v19
	v_cvt_pk_bf16_f32 v0, v0, v1
	v_cvt_pk_bf16_f32 v1, v2, v3
	v_cvt_pk_bf16_f32 v18, v20, v21
	v_cvt_pk_bf16_f32 v19, v22, v23
	v_cvt_pk_bf16_f32 v20, v24, v25
	v_cvt_pk_bf16_f32 v21, v26, v27
	v_cvt_pk_bf16_f32 v22, v28, v29
	v_cvt_pk_bf16_f32 v23, v30, v31
	global_store_dwordx2 v[140:141], v[16:17], off
	global_store_dwordx2 v[140:141], v[18:19], off offset:16
	global_store_dwordx2 v[140:141], v[20:21], off offset:32
	global_store_dwordx2 v[140:141], v[22:23], off offset:48
	global_store_dwordx2 v[140:141], v[0:1], off offset:64
	s_waitcnt vmcnt(7)
	v_lshlrev_b32_e32 v0, 16, v42
	v_and_b32_e32 v1, 0xffff0000, v42
	v_lshlrev_b32_e32 v2, 16, v43
	v_and_b32_e32 v3, 0xffff0000, v43
	v_pk_fma_f32 v[0:1], v[4:5], v[44:45], v[0:1] op_sel_hi:[1,0,1]
	v_pk_fma_f32 v[2:3], v[6:7], v[44:45], v[2:3] op_sel_hi:[1,0,1]
	v_cvt_pk_bf16_f32 v0, v0, v1
	v_cvt_pk_bf16_f32 v1, v2, v3
	global_store_dwordx2 v[140:141], v[0:1], off offset:80
	s_waitcnt vmcnt(7)
	v_lshlrev_b32_e32 v0, 16, v46
	v_and_b32_e32 v1, 0xffff0000, v46
	v_lshlrev_b32_e32 v2, 16, v47
	v_and_b32_e32 v3, 0xffff0000, v47
	v_pk_fma_f32 v[0:1], v[8:9], v[44:45], v[0:1] op_sel_hi:[1,0,1]
	v_pk_fma_f32 v[2:3], v[10:11], v[44:45], v[2:3] op_sel_hi:[1,0,1]
	v_cvt_pk_bf16_f32 v0, v0, v1
	v_cvt_pk_bf16_f32 v1, v2, v3
	global_store_dwordx2 v[140:141], v[0:1], off offset:96
	s_waitcnt vmcnt(7)
	v_lshlrev_b32_e32 v0, 16, v48
	v_and_b32_e32 v1, 0xffff0000, v48
	v_lshlrev_b32_e32 v2, 16, v49
	v_and_b32_e32 v3, 0xffff0000, v49
	v_pk_fma_f32 v[0:1], v[12:13], v[44:45], v[0:1] op_sel_hi:[1,0,1]
	v_pk_fma_f32 v[2:3], v[14:15], v[44:45], v[2:3] op_sel_hi:[1,0,1]
	v_cvt_pk_bf16_f32 v0, v0, v1
	v_cvt_pk_bf16_f32 v1, v2, v3
	global_store_dwordx2 v[140:141], v[0:1], off offset:112
	v_mov_b64_e32 v[0:1], s[36:37]
	v_readfirstlane_b32 s0, v74
	s_ashr_i32 s0, s0, 6
	s_lshl_b32 s16, s0, 3
	v_and_b32_e32 v63, 3, v74
	s_add_i32 s96, s16, s68
	v_bfe_u32 v75, v74, 2, 3
	v_or_b32_e32 v136, s96, v75
	v_lshl_or_b32 v62, v63, 6, s34
	v_bfe_u32 v77, v74, 5, 1
	v_mad_i64_i32 v[36:37], s[6:7], v136, s3, v[0:1]
	v_lshlrev_b32_e32 v160, 1, v62
	v_lshl_add_u64 v[0:1], v[36:37], 0, v[160:161]
	v_lshlrev_b32_e32 v60, 4, v77
	v_lshl_add_u64 v[0:1], v[0:1], 0, v[60:61]
	s_barrier
; DI float bf1(bf16_t v) { return __uint_as_float(((unsigned)v) << 16); }
; DI void unpack8(const u32x4 w, float (&f)[8]) { f[0] = bflo(w.x); f[1] = bfhi(w.x); f[2] = bflo(w.y); f[3] = bfhi(w.y); f[4] = bflo(w.z); f[5] = bfhi(w.z); f[6] = bflo(w.w); f[7] = bfhi(w.w); }
; DI u32x4 pack8(const float (&f)[8]) { u32x4 w; w.x = cvtpk(f[0], f[1]); w.y = cvtpk(f[2], f[3]); w.z = cvtpk(f[4], f[5]); w.w = cvtpk(f[6], f[7]); return w; }
; DI void nsa_wg_unit(const Args& a, int l, int b, int g, int tb, unsigned char* lds, int tid_in, bool stage) {
;     ...
;     { const bf16_t* zr = zb + (size_t)tk[0] * ZP;
; #pragma unroll
;       for (int dc = 0; dc < 4; ++dc) qf[0][dc] = *(const bf16x8*)(zr + C_Q + (g * 4 + head) * 64 + dc * 16 + 8 * h);
;       { const float* qg = a.in[4] + (size_t)l * 4 * 64; float qv[4][8]; float qs = 0.f;
; #pragma unroll
;         for (int dc = 0; dc < 4; ++dc) { unpack8(__builtin_bit_cast(u32x4, qf[0][dc]), qv[dc]);
; #pragma unroll
;             for (int e = 0; e < 8; ++e) qs += qv[dc][e] * qv[dc][e]; }
;         qs += __shfl_xor(qs, 32); const float rs = rsqrtf(qs * (1.0f / 64.0f) + 1e-6f) * QSC;
; #pragma unroll
;         for (int dc = 0; dc < 4; ++dc) { const f32x4 g0 = *(const f32x4*)(qg + dc * 16 + 8 * h), g1 = *(const f32x4*)(qg + dc * 16 + 8 * h + 4);
; #pragma unroll
;             for (int e = 0; e < 4; ++e) { qv[dc][e] = qv[dc][e] * rs * g0[e]; qv[dc][4 + e] = qv[dc][4 + e] * rs * g1[e]; }
;             qf[0][dc] = __builtin_bit_cast(bf16x8, pack8(qv[dc])); } }
; #pragma unroll
;       for (int br = 0; br < 3; ++br) gt[0][br] = 1.0f / (1.0f + __expf(-bf1(zr[C_NG + (g * 4 + head) * 3 + br])));
;       orow[0] = OB + ((size_t)b * SEQ + tk[0]) * 512 + (g * 4 + head) * 64 + 4 * h; }
;     float cref[3];
;     { const float* qg = a.in[4] + (size_t)l * 4 * 64; float mx[4];
; #pragma unroll
;       for (int k4 = 0; k4 < 4; ++k4) { float v = fabsf(qg[k4 * 64 + lane]);
	global_load_dwordx4 v[46:49], v[0:1], off offset:3168
	global_load_dwordx4 v[54:57], v[0:1], off offset:3136
	global_load_dwordx4 v[66:69], v[0:1], off offset:3104
	global_load_dwordx4 v[32:35], v[0:1], off offset:3072
	v_and_b32_e32 v76, 63, v74
	v_and_b32_e32 v4, 32, v74
	v_lshlrev_b32_e32 v108, 2, v76
	global_load_dwordx4 v[24:27], v4, s[90:91] offset:16
	global_load_dwordx4 v[28:31], v4, s[90:91]
	global_load_dwordx4 v[16:19], v4, s[90:91] offset:80
	global_load_dwordx4 v[20:23], v4, s[90:91] offset:64
	global_load_dwordx4 v[8:11], v4, s[90:91] offset:144
	global_load_dwordx4 v[12:15], v4, s[90:91] offset:128
	global_load_dwordx4 v[0:3], v4, s[90:91] offset:208
	s_nop 0
	global_load_dwordx4 v[4:7], v4, s[90:91] offset:192
	s_mov_b64 s[6:7], 0x1600
	global_load_dword v61, v108, s[90:91]
	global_load_dword v109, v108, s[90:91] offset:256
	global_load_dword v110, v108, s[90:91] offset:512
	global_load_dword v111, v108, s[90:91] offset:768
	s_mulk_i32 s0, 0x1080
	s_add_i32 s8, s0, 0
	s_add_i32 s9, s8, 0x19e00
	v_and_b32_e32 v72, 31, v74
	v_lshlrev_b32_e32 v73, 3, v77
	v_ashrrev_i32_e32 v137, 31, v136
	s_mov_b64 s[0:1], 0
	s_waitcnt vmcnt(15)
	v_lshlrev_b32_e32 v40, 16, v47
	v_and_b32_e32 v41, 0xffff0000, v47
	v_lshlrev_b32_e32 v44, 16, v46
	v_and_b32_e32 v45, 0xffff0000, v46
	s_waitcnt vmcnt(14)
	v_lshlrev_b32_e32 v46, 16, v57
	v_and_b32_e32 v47, 0xffff0000, v57
	v_lshlrev_b32_e32 v50, 16, v56
	v_and_b32_e32 v51, 0xffff0000, v56
	s_waitcnt vmcnt(13)
	v_lshlrev_b32_e32 v56, 16, v67
	v_and_b32_e32 v57, 0xffff0000, v67
	v_lshlrev_b32_e32 v64, 16, v66
	v_and_b32_e32 v65, 0xffff0000, v66
	s_waitcnt vmcnt(12)
	v_lshlrev_b32_e32 v66, 16, v35
	v_and_b32_e32 v67, 0xffff0000, v35
	v_lshlrev_b32_e32 v70, 16, v34
	v_and_b32_e32 v71, 0xffff0000, v34
	v_lshlrev_b32_e32 v34, 16, v32
	v_and_b32_e32 v35, 0xffff0000, v32
	v_lshlrev_b32_e32 v38, 16, v49
	v_and_b32_e32 v39, 0xffff0000, v49
	v_lshlrev_b32_e32 v42, 16, v48
	v_and_b32_e32 v43, 0xffff0000, v48
	v_lshlrev_b32_e32 v48, 16, v55
	v_and_b32_e32 v49, 0xffff0000, v55
	v_lshlrev_b32_e32 v52, 16, v54
	v_and_b32_e32 v53, 0xffff0000, v54
	v_lshlrev_b32_e32 v54, 16, v69
	v_and_b32_e32 v55, 0xffff0000, v69
	v_lshlrev_b32_e32 v58, 16, v68
	v_and_b32_e32 v59, 0xffff0000, v68
	v_lshlrev_b32_e32 v68, 16, v33
	v_and_b32_e32 v69, 0xffff0000, v33
	v_pk_mul_f32 v[32:33], v[34:35], v[34:35]
	v_pk_mul_f32 v[104:105], v[68:69], v[68:69]
	v_add_f32_e32 v32, v32, v33
	v_add_f32_e32 v32, v104, v32
	v_pk_mul_f32 v[106:107], v[70:71], v[70:71]
	v_add_f32_e32 v32, v105, v32
	v_add_f32_e32 v32, v106, v32
	v_pk_mul_f32 v[102:103], v[66:67], v[66:67]
	v_add_f32_e32 v32, v107, v32
	v_add_f32_e32 v32, v102, v32
	v_pk_mul_f32 v[100:101], v[64:65], v[64:65]
	v_add_f32_e32 v32, v103, v32
	v_add_f32_e32 v32, v100, v32
	v_pk_mul_f32 v[96:97], v[56:57], v[56:57]
	v_add_f32_e32 v32, v101, v32
	v_add_f32_e32 v32, v96, v32
	v_pk_mul_f32 v[98:99], v[58:59], v[58:59]
	v_add_f32_e32 v32, v97, v32
	v_add_f32_e32 v32, v98, v32
	v_pk_mul_f32 v[94:95], v[54:55], v[54:55]
	v_add_f32_e32 v32, v99, v32
	v_add_f32_e32 v32, v94, v32
	v_pk_mul_f32 v[92:93], v[52:53], v[52:53]
	v_add_f32_e32 v32, v95, v32
	v_add_f32_e32 v32, v92, v32
	v_pk_mul_f32 v[88:89], v[48:49], v[48:49]
	v_add_f32_e32 v32, v93, v32
	v_add_f32_e32 v32, v88, v32
	v_pk_mul_f32 v[90:91], v[50:51], v[50:51]
	v_add_f32_e32 v32, v89, v32
	v_add_f32_e32 v32, v90, v32
	v_pk_mul_f32 v[86:87], v[46:47], v[46:47]
	v_add_f32_e32 v32, v91, v32
	v_add_f32_e32 v32, v86, v32
	v_pk_mul_f32 v[84:85], v[44:45], v[44:45]
	v_add_f32_e32 v32, v87, v32
	v_add_f32_e32 v32, v84, v32
	v_pk_mul_f32 v[80:81], v[40:41], v[40:41]
	v_add_f32_e32 v32, v85, v32
	v_add_f32_e32 v32, v80, v32
	v_add_f32_e32 v80, v81, v32
	v_or_b32_e32 v32, s29, v63
	v_mul_u32_u24_e32 v32, 3, v32
	v_lshlrev_b32_e32 v160, 1, v32
	v_lshl_add_u64 v[32:33], v[36:37], 0, v[160:161]
	v_lshl_add_u64 v[36:37], v[32:33], 0, s[6:7]
	v_add_co_u32_e32 v32, vcc, s17, v32
	s_waitcnt vmcnt(3)
; DI float bf1(bf16_t v) { return __uint_as_float(((unsigned)v) << 16); }
; DI u32x4 pack8(const float (&f)[8]) { u32x4 w; w.x = cvtpk(f[0], f[1]); w.y = cvtpk(f[2], f[3]); w.z = cvtpk(f[4], f[5]); w.w = cvtpk(f[6], f[7]); return w; }
; DI void nsa_wg_unit(const Args& a, int l, int b, int g, int tb, unsigned char* lds, int tid_in, bool stage) {
;     ...
;         qs += __shfl_xor(qs, 32); const float rs = rsqrtf(qs * (1.0f / 64.0f) + 1e-6f) * QSC;
; #pragma unroll
;         for (int dc = 0; dc < 4; ++dc) { const f32x4 g0 = *(const f32x4*)(qg + dc * 16 + 8 * h), g1 = *(const f32x4*)(qg + dc * 16 + 8 * h + 4);
; #pragma unroll
;             for (int e = 0; e < 4; ++e) { qv[dc][e] = qv[dc][e] * rs * g0[e]; qv[dc][4 + e] = qv[dc][4 + e] * rs * g1[e]; }
;             qf[0][dc] = __builtin_bit_cast(bf16x8, pack8(qv[dc])); } }
; #pragma unroll
;       for (int br = 0; br < 3; ++br) gt[0][br] = 1.0f / (1.0f + __expf(-bf1(zr[C_NG + (g * 4 + head) * 3 + br])));
;       orow[0] = OB + ((size_t)b * SEQ + tk[0]) * 512 + (g * 4 + head) * 64 + 4 * h; }
;     float cref[3];
;     { const float* qg = a.in[4] + (size_t)l * 4 * 64; float mx[4];
; #pragma unroll
;       for (int k4 = 0; k4 < 4; ++k4) { float v = fabsf(qg[k4 * 64 + lane]);
; #pragma unroll
;           for (int o = 1; o < 64; o <<= 1) v = fmaxf(v, __shfl_xor(v, o));
;           mx[k4] = v; }
; #pragma unroll
;       for (int br = 0; br < 3; ++br) { const float bnd = 64.0f * QSC * mx[0] * mx[1 + br]; cref[br] = bnd > 64.0f ? bnd : 0.f; } }
	v_and_b32_e32 v81, 0x7fffffff, v61
	v_addc_co_u32_e32 v33, vcc, 0, v33, vcc
	global_load_dword v32, v[32:33], off offset:1536
	s_nop 0
	global_load_ushort v139, v[36:37], off offset:4
	ds_bpermute_b32 v81, v152, v81
	v_max_f32_e64 v33, |v61|, |v61|
	s_waitcnt vmcnt(4)
	v_and_b32_e32 v61, 0x7fffffff, v109
	ds_bpermute_b32 v61, v152, v61
	v_pk_mul_f32 v[82:83], v[42:43], v[42:43]
	s_waitcnt lgkmcnt(1)
	v_max_f32_e32 v36, v81, v81
	v_max_f32_e32 v33, v33, v36
	ds_bpermute_b32 v36, v153, v33
	v_add_f32_e32 v37, v82, v80
	v_max_f32_e64 v80, |v109|, |v109|
	s_waitcnt lgkmcnt(1)
	v_max_f32_e32 v61, v61, v61
	v_max_f32_e32 v61, v80, v61
	s_waitcnt lgkmcnt(0)
	v_max_f32_e32 v36, v36, v36
	v_max_f32_e32 v33, v33, v36
	ds_bpermute_b32 v36, v154, v33
	ds_bpermute_b32 v80, v153, v61
	v_pk_mul_f32 v[78:79], v[38:39], v[38:39]
	v_add_f32_e32 v37, v83, v37
	v_add_f32_e32 v37, v78, v37
	s_waitcnt lgkmcnt(1)
	v_max_f32_e32 v36, v36, v36
	v_max_f32_e32 v33, v33, v36
	ds_bpermute_b32 v36, v150, v33
	s_waitcnt lgkmcnt(1)
	v_max_f32_e32 v78, v80, v80
	v_max_f32_e32 v61, v61, v78
	ds_bpermute_b32 v78, v154, v61
	v_add_f32_e32 v80, v79, v37
	s_waitcnt lgkmcnt(1)
	v_max_f32_e32 v36, v36, v36
	v_max_f32_e32 v33, v33, v36
	ds_bpermute_b32 v36, v151, v33
	s_waitcnt lgkmcnt(1)
	v_max_f32_e32 v37, v78, v78
	v_max_f32_e32 v37, v61, v37
	ds_bpermute_b32 v61, v150, v37
	s_waitcnt vmcnt(2)
	v_max_f32_e64 v82, |v111|, |v111|
	s_waitcnt lgkmcnt(1)
	v_max_f32_e32 v36, v36, v36
	v_max_f32_e32 v78, v33, v36
	v_and_b32_e32 v36, 0x7fffffff, v110
	s_waitcnt lgkmcnt(0)
	v_max_f32_e32 v33, v61, v61
	ds_bpermute_b32 v36, v152, v36
	v_and_b32_e32 v61, 0x7fffffff, v111
	ds_bpermute_b32 v61, v152, v61
	v_max_f32_e32 v33, v37, v33
	v_max_f32_e64 v37, |v110|, |v110|
	s_waitcnt lgkmcnt(1)
	v_max_f32_e32 v36, v36, v36
	v_max_f32_e32 v36, v37, v36
	s_waitcnt lgkmcnt(0)
	v_max_f32_e32 v61, v61, v61
	ds_bpermute_b32 v37, v153, v36
	v_max_f32_e32 v61, v82, v61
	ds_bpermute_b32 v82, v153, v61
	ds_bpermute_b32 v83, v151, v33
	ds_bpermute_b32 v81, v148, v80
	s_waitcnt lgkmcnt(3)
	v_max_f32_e32 v37, v37, v37
	v_max_f32_e32 v36, v36, v37
	s_waitcnt lgkmcnt(2)
	v_max_f32_e32 v82, v82, v82
	ds_bpermute_b32 v37, v154, v36
	v_max_f32_e32 v61, v61, v82
	ds_bpermute_b32 v82, v154, v61
	s_waitcnt lgkmcnt(3)
	v_max_f32_e32 v83, v83, v83
	v_max_f32_e32 v96, v33, v83
	s_waitcnt lgkmcnt(1)
	v_max_f32_e32 v37, v37, v37
	v_max_f32_e32 v36, v36, v37
	s_waitcnt lgkmcnt(0)
	v_max_f32_e32 v82, v82, v82
	ds_bpermute_b32 v37, v150, v36
	v_max_f32_e32 v61, v61, v82
	ds_bpermute_b32 v82, v150, v61
	ds_bpermute_b32 v79, v148, v78
	ds_bpermute_b32 v97, v148, v96
	s_waitcnt lgkmcnt(3)
	v_max_f32_e32 v33, v37, v37
	v_max_f32_e32 v33, v36, v33
	s_waitcnt lgkmcnt(2)
	v_max_f32_e32 v37, v82, v82
	ds_bpermute_b32 v36, v151, v33
	v_max_f32_e32 v61, v61, v37
	ds_bpermute_b32 v82, v151, v61
	v_add_u32_e32 v83, s9, v108
	s_waitcnt lgkmcnt(1)
	v_max_f32_e32 v36, v36, v36
	v_max_f32_e32 v33, v33, v36
	s_waitcnt lgkmcnt(0)
	v_max_f32_e32 v36, v82, v82
	v_max_f32_e32 v36, v61, v36
	ds_bpermute_b32 v37, v148, v33
	ds_bpermute_b32 v61, v148, v36
	v_or_b32_e32 v82, 0xffffffc0, v76

; #define LDS_FENCE() asm volatile("s_waitcnt lgkmcnt(0)" ::: "memory")
; DI void nsa_wg_unit(const Args& a, int l, int b, int g, int tb, unsigned char* lds, int tid_in, bool stage) {
;     ...
;     { float sc[NRT]; sc[0] = gt[0][0]; attn_flush<true>(st, sc, orow); }
;     LDS_FENCE();
;     unsigned sel_lo[NRT], sel_hi[NRT], ulo, uhi;
;     { const int tok = lane / LPT, qtr = lane % LPT; float mv[CPL];
; #pragma unroll
;       for (int c = 0; c < CPL; ++c) { const int j = qtr * CPL + c; float v = IA[tok * 65 + j] + IB[tok * 65 + j]; const bool forced = (j == 0) | (j == jt) | (j == jt - 1); v = forced ? 1e6f : (j > jt ? -1e30f : v); mv[c] = v; }
.LBB0_217:
	v_add_f32_e32 v34, 1.0, v78
	v_div_scale_f32 v35, s[0:1], v34, v34, 1.0
	v_rcp_f32_e32 v36, v35
	v_lshlrev_b64 v[32:33], 10, v[136:137]
	v_lshl_add_u64 v[32:33], s[42:43], 0, v[32:33]
	v_lshlrev_b32_e32 v160, 1, v62
	v_fma_f32 v37, -v35, v36, 1.0
	v_fmac_f32_e32 v36, v37, v36
	v_div_scale_f32 v37, vcc, 1.0, v34, 1.0
	v_mul_f32_e32 v38, v37, v36
	v_fma_f32 v39, -v35, v38, v37
	v_fmac_f32_e32 v38, v39, v36
	v_fma_f32 v35, -v35, v38, v37
	v_div_fmas_f32 v35, v35, v36, v38
	v_div_fixup_f32 v34, v35, v34, 1.0
	v_lshl_add_u64 v[32:33], v[32:33], 0, v[160:161]
	v_lshlrev_b32_e32 v160, 1, v154
	v_pk_mul_f32 v[16:17], v[34:35], v[16:17] op_sel_hi:[0,1]
	v_pk_mul_f32 v[18:19], v[34:35], v[18:19] op_sel_hi:[0,1]
	v_pk_mul_f32 v[0:1], v[34:35], v[0:1] op_sel_hi:[0,1]
	v_pk_mul_f32 v[2:3], v[34:35], v[2:3] op_sel_hi:[0,1]
	v_lshl_add_u64 v[140:141], v[32:33], 0, v[160:161]
	v_cvt_pk_bf16_f32 v16, v16, v17
	v_cvt_pk_bf16_f32 v17, v18, v19
	v_cvt_pk_bf16_f32 v0, v0, v1
	v_cvt_pk_bf16_f32 v1, v2, v3
	v_mov_b64_e32 v[236:237], v[16:17]
	v_pk_mul_f32 v[16:17], v[34:35], v[20:21] op_sel_hi:[0,1]
	v_pk_mul_f32 v[18:19], v[34:35], v[22:23] op_sel_hi:[0,1]
	v_mov_b64_e32 v[244:245], v[0:1]
	v_pk_mul_f32 v[0:1], v[34:35], v[4:5] op_sel_hi:[0,1]
	v_pk_mul_f32 v[2:3], v[34:35], v[6:7] op_sel_hi:[0,1]
	v_cvt_pk_bf16_f32 v16, v16, v17
	v_cvt_pk_bf16_f32 v17, v18, v19
	v_cvt_pk_bf16_f32 v0, v0, v1
	v_cvt_pk_bf16_f32 v1, v2, v3
	v_mov_b64_e32 v[238:239], v[16:17]
	v_pk_mul_f32 v[16:17], v[34:35], v[24:25] op_sel_hi:[0,1]
	v_pk_mul_f32 v[18:19], v[34:35], v[26:27] op_sel_hi:[0,1]
	v_mov_b64_e32 v[246:247], v[0:1]
	v_pk_mul_f32 v[0:1], v[34:35], v[8:9] op_sel_hi:[0,1]
	v_pk_mul_f32 v[2:3], v[34:35], v[10:11] op_sel_hi:[0,1]
	v_cvt_pk_bf16_f32 v16, v16, v17
	v_cvt_pk_bf16_f32 v17, v18, v19
	v_cvt_pk_bf16_f32 v0, v0, v1
	v_cvt_pk_bf16_f32 v1, v2, v3
	v_mov_b64_e32 v[240:241], v[16:17]
	v_pk_mul_f32 v[16:17], v[34:35], v[28:29] op_sel_hi:[0,1]
	v_pk_mul_f32 v[18:19], v[34:35], v[30:31] op_sel_hi:[0,1]
	v_mov_b64_e32 v[248:249], v[0:1]
	v_pk_mul_f32 v[0:1], v[34:35], v[12:13] op_sel_hi:[0,1]
	v_pk_mul_f32 v[2:3], v[34:35], v[14:15] op_sel_hi:[0,1]
	v_cvt_pk_bf16_f32 v16, v16, v17
	v_cvt_pk_bf16_f32 v17, v18, v19
	v_cvt_pk_bf16_f32 v0, v0, v1
	v_cvt_pk_bf16_f32 v1, v2, v3
	v_and_b32_e32 v32, 7, v74
	v_mov_b64_e32 v[242:243], v[16:17]
	v_mov_b64_e32 v[250:251], v[0:1]
	v_lshlrev_b32_e32 v0, 3, v32
	s_waitcnt lgkmcnt(0)
	s_sub_i32 s10, 62, s33
	v_cmp_ne_u32_e32 vcc, 0, v32
	v_cmp_ne_u32_e64 s[6:7], s93, v0
	v_lshrrev_b32_e32 v30, 3, v76
	s_and_b64 s[0:1], vcc, s[6:7]
	v_cmp_ne_u32_e32 vcc, s10, v0
	v_mul_u32_u24_e32 v1, 0x41, v30
	s_and_b64 s[6:7], vcc, s[0:1]
	v_mov_b32_e32 v2, 0x49742400
	v_mov_b32_e32 v4, 0x49742400
	s_and_saveexec_b64 s[0:1], s[6:7]
	s_cbranch_execz .LBB0_219
	v_add_u32_e32 v3, v1, v0
	v_lshl_add_u32 v3, v3, 2, s9
	ds_read_b32 v4, v3
	ds_read_b32 v3, v3 offset:2080
	v_cmp_ge_u32_e32 vcc, s93, v0
	s_waitcnt lgkmcnt(0)
	v_add_f32_e32 v3, v4, v3
	v_cndmask_b32_e32 v4, v219, v3, vcc

; DI void nsa_wg_unit(const Args& a, int l, int b, int g, int tb, unsigned char* lds, int tid_in, bool stage) {
;     ...
;     { float sc[NRT]; const float lt = st.l[0] + __shfl_xor(st.l[0], 32); sc[0] = lt > 0.f ? gt[0][1] / lt : 0.f; attn_flush<false>(st, sc, orow); }
;     attn_reset(st);
;     { const unsigned koff = (unsigned)(srow * ZP + sch * 8) * 2u, voff = (unsigned)(srow * SEQ + sch * 8) * 2u; const char* kgb = (const char*)(zb + C_KV + 4 * 128 + g * 64); const char* vgb = (const char*)VWT;
;       int j = tb - 8 < 0 ? 0 : tb - 8, bi = 0; u32x4 kreg, vreg;
;       { kreg = *(const u32x4*)(kgb + (size_t)(64 * j) * ZP * 2 + koff); vreg = *(const u32x4*)(vgb + (size_t)(64 * j) * 2 + voff);
;         *(u32x4*)(lds + AL_KR + srow * KR_PB + sch * 16) = kreg; u32x2* d = (u32x2*)(lds + AL_VR + srow * VR_PB + sch * 16); u32x2 lo2, hi2; lo2.x = vreg.x; lo2.y = vreg.y; hi2.x = vreg.z; hi2.y = vreg.w; d[0] = lo2; d[1] = hi2; }
;       __syncthreads();
.LBB0_259:
	v_mov_b64_e32 v[32:33], v[236:237]
	v_mov_b64_e32 v[34:35], v[238:239]
	v_mov_b64_e32 v[36:37], v[240:241]
	v_mov_b64_e32 v[38:39], v[242:243]
	v_mov_b64_e32 v[40:41], v[244:245]
	v_mov_b64_e32 v[42:43], v[246:247]
	v_mov_b64_e32 v[44:45], v[248:249]
	v_mov_b64_e32 v[46:47], v[250:251]
	v_add_f32_e32 v48, 1.0, v158
	v_div_scale_f32 v50, s[0:1], v48, v48, 1.0
	v_rcp_f32_e32 v51, v50
	v_div_scale_f32 v52, vcc, 1.0, v48, 1.0
	ds_bpermute_b32 v49, v148, v155
	v_fma_f32 v53, -v50, v51, 1.0
	v_fmac_f32_e32 v51, v53, v51
	v_mul_f32_e32 v53, v52, v51
	v_fma_f32 v54, -v50, v53, v52
	v_fmac_f32_e32 v53, v54, v51
	v_fma_f32 v50, -v50, v53, v52
	v_div_fmas_f32 v50, v50, v51, v53
	s_waitcnt lgkmcnt(0)
	v_add_f32_e32 v49, v155, v49
	v_div_fixup_f32 v48, v50, v48, 1.0
	v_div_scale_f32 v50, s[0:1], v49, v49, v48
	v_rcp_f32_e32 v51, v50
	v_div_scale_f32 v52, vcc, v48, v49, v48
	s_sub_i32 s10, 55, s33
	v_fma_f32 v53, -v50, v51, 1.0
	v_fmac_f32_e32 v51, v53, v51
	v_mul_f32_e32 v53, v52, v51
	v_fma_f32 v54, -v50, v53, v52
	v_fmac_f32_e32 v53, v54, v51
	v_fma_f32 v50, -v50, v53, v52
	v_div_fmas_f32 v50, v50, v51, v53
	v_div_fixup_f32 v48, v50, v49, v48
	v_cmp_lt_f32_e32 vcc, 0, v49
	s_mul_i32 s0, s10, 0x88c00
	s_add_u32 s0, s45, s0
	v_cndmask_b32_e32 v48, 0, v48, vcc
	s_addc_u32 s1, s46, 0
	v_add3_u32 v146, s26, v137, v138
	v_add3_u32 v138, s28, v151, v138
	s_waitcnt vmcnt(7)
	v_lshlrev_b32_e32 v50, 16, v32
	v_and_b32_e32 v51, 0xffff0000, v32
	v_lshlrev_b32_e32 v32, 16, v33
	v_and_b32_e32 v33, 0xffff0000, v33
	s_waitcnt vmcnt(3)
	v_lshlrev_b32_e32 v58, 16, v40
	v_and_b32_e32 v59, 0xffff0000, v40
	v_lshlrev_b32_e32 v40, 16, v41
	v_and_b32_e32 v41, 0xffff0000, v41
	v_lshlrev_b32_e32 v52, 16, v34
	v_and_b32_e32 v53, 0xffff0000, v34
	v_lshlrev_b32_e32 v34, 16, v35
	v_and_b32_e32 v35, 0xffff0000, v35
	v_lshlrev_b32_e32 v54, 16, v36
	v_and_b32_e32 v55, 0xffff0000, v36
	v_lshlrev_b32_e32 v36, 16, v37
	v_and_b32_e32 v37, 0xffff0000, v37
	v_lshlrev_b32_e32 v56, 16, v38
	v_and_b32_e32 v57, 0xffff0000, v38
	v_lshlrev_b32_e32 v38, 16, v39
	v_and_b32_e32 v39, 0xffff0000, v39
	v_pk_fma_f32 v[16:17], v[16:17], v[48:49], v[50:51] op_sel_hi:[1,0,1]
	v_pk_fma_f32 v[18:19], v[18:19], v[48:49], v[32:33] op_sel_hi:[1,0,1]
	v_pk_fma_f32 v[0:1], v[0:1], v[48:49], v[58:59] op_sel_hi:[1,0,1]
	v_pk_fma_f32 v[2:3], v[2:3], v[48:49], v[40:41] op_sel_hi:[1,0,1]
	v_pk_fma_f32 v[20:21], v[20:21], v[48:49], v[52:53] op_sel_hi:[1,0,1]
	v_pk_fma_f32 v[22:23], v[22:23], v[48:49], v[34:35] op_sel_hi:[1,0,1]
	v_pk_fma_f32 v[24:25], v[24:25], v[48:49], v[54:55] op_sel_hi:[1,0,1]
	v_pk_fma_f32 v[26:27], v[26:27], v[48:49], v[36:37] op_sel_hi:[1,0,1]
	v_pk_fma_f32 v[28:29], v[28:29], v[48:49], v[56:57] op_sel_hi:[1,0,1]
	v_pk_fma_f32 v[30:31], v[30:31], v[48:49], v[38:39] op_sel_hi:[1,0,1]
	v_cvt_pk_bf16_f32 v16, v16, v17
	v_cvt_pk_bf16_f32 v17, v18, v19
	v_cvt_pk_bf16_f32 v0, v0, v1
	v_cvt_pk_bf16_f32 v1, v2, v3
	v_cvt_pk_bf16_f32 v18, v20, v21
	v_cvt_pk_bf16_f32 v19, v22, v23
	v_cvt_pk_bf16_f32 v20, v24, v25
	v_cvt_pk_bf16_f32 v21, v26, v27
	v_cvt_pk_bf16_f32 v22, v28, v29
	v_cvt_pk_bf16_f32 v23, v30, v31
	v_mov_b64_e32 v[236:237], v[16:17]
	v_mov_b64_e32 v[238:239], v[18:19]
	v_mov_b64_e32 v[240:241], v[20:21]
	v_mov_b64_e32 v[242:243], v[22:23]
	v_mov_b64_e32 v[244:245], v[0:1]
	s_waitcnt vmcnt(7)
	v_lshlrev_b32_e32 v0, 16, v42
	v_and_b32_e32 v1, 0xffff0000, v42
	v_lshlrev_b32_e32 v2, 16, v43
	v_and_b32_e32 v3, 0xffff0000, v43
	v_pk_fma_f32 v[0:1], v[4:5], v[48:49], v[0:1] op_sel_hi:[1,0,1]
	v_pk_fma_f32 v[2:3], v[6:7], v[48:49], v[2:3] op_sel_hi:[1,0,1]
	v_cvt_pk_bf16_f32 v0, v0, v1
	v_cvt_pk_bf16_f32 v1, v2, v3
	v_mov_b64_e32 v[246:247], v[0:1]
	s_waitcnt vmcnt(7)
	v_lshlrev_b32_e32 v0, 16, v44
	v_and_b32_e32 v1, 0xffff0000, v44
	v_lshlrev_b32_e32 v2, 16, v45
	v_and_b32_e32 v3, 0xffff0000, v45
	v_pk_fma_f32 v[0:1], v[8:9], v[48:49], v[0:1] op_sel_hi:[1,0,1]
	v_pk_fma_f32 v[2:3], v[10:11], v[48:49], v[2:3] op_sel_hi:[1,0,1]
	v_cvt_pk_bf16_f32 v0, v0, v1
	v_cvt_pk_bf16_f32 v1, v2, v3
	v_mov_b64_e32 v[248:249], v[0:1]
	s_waitcnt vmcnt(7)
	v_lshlrev_b32_e32 v0, 16, v46
	v_and_b32_e32 v1, 0xffff0000, v46
	v_lshlrev_b32_e32 v2, 16, v47
	v_and_b32_e32 v3, 0xffff0000, v47
	v_pk_fma_f32 v[0:1], v[12:13], v[48:49], v[0:1] op_sel_hi:[1,0,1]
	v_pk_fma_f32 v[2:3], v[14:15], v[48:49], v[2:3] op_sel_hi:[1,0,1]
	v_cvt_pk_bf16_f32 v0, v0, v1
	v_cvt_pk_bf16_f32 v1, v2, v3
	v_mov_b64_e32 v[250:251], v[0:1]
	v_lshl_add_u64 v[0:1], s[0:1], 0, v[142:143]
	s_lshl_b32 s0, s10, 7
	s_add_u32 s0, s2, s0
	s_addc_u32 s1, s35, 0
	v_lshl_add_u64 v[2:3], s[0:1], 0, v[160:161]
	global_load_dwordx4 v[96:99], v[0:1], off
	global_load_dwordx4 v[100:103], v[2:3], off
	v_mov_b32_e32 v15, 0
	v_mov_b32_e32 v14, v15
	v_mov_b32_e32 v13, v15
	v_mov_b32_e32 v12, v15
	v_mov_b32_e32 v11, v15
	v_mov_b32_e32 v10, v15
	v_mov_b32_e32 v9, v15
	v_mov_b32_e32 v8, v15
	v_mov_b32_e32 v7, v15
	v_mov_b32_e32 v6, v15
	v_mov_b32_e32 v5, v15
	v_mov_b32_e32 v4, v15
	v_mov_b32_e32 v3, v15
	v_mov_b32_e32 v2, v15
	v_mov_b32_e32 v1, v15
	v_mov_b32_e32 v0, v15
	v_mov_b32_e32 v31, v15
	v_mov_b32_e32 v30, v15
	v_mov_b32_e32 v29, v15
	v_mov_b32_e32 v28, v15
	v_mov_b32_e32 v27, v15
	v_mov_b32_e32 v26, v15
	v_mov_b32_e32 v25, v15
	v_mov_b32_e32 v24, v15
	v_mov_b32_e32 v23, v15
	v_mov_b32_e32 v22, v15
	v_mov_b32_e32 v21, v15
	v_mov_b32_e32 v20, v15
	v_mov_b32_e32 v19, v15
	v_mov_b32_e32 v18, v15
	v_mov_b32_e32 v17, v15
	v_mov_b32_e32 v16, v15
	s_cmp_gt_u32 s10, s93
	v_mov_b32_e32 v137, v15
	s_waitcnt vmcnt(1)
	ds_write_b128 v146, v[96:99]
	s_waitcnt vmcnt(0)
	ds_write2_b64 v138, v[100:101], v[102:103] offset1:1
	s_waitcnt lgkmcnt(0)
	s_barrier
; DI void nsa_wg_unit(const Args& a, int l, int b, int g, int tb, unsigned char* lds, int tid_in, bool stage) {
;     ...
;     { const unsigned koff = (unsigned)(srow * ZP + sch * 8) * 2u, voff = (unsigned)(srow * SEQ + sch * 8) * 2u; const char* kgb = (const char*)(zb + C_KV + 4 * 128 + g * 64); const char* vgb = (const char*)VWT;
;       int j = tb - 8 < 0 ? 0 : tb - 8, bi = 0; u32x4 kreg, vreg;
;       { kreg = *(const u32x4*)(kgb + (size_t)(64 * j) * ZP * 2 + koff); vreg = *(const u32x4*)(vgb + (size_t)(64 * j) * 2 + voff);
;         *(u32x4*)(lds + AL_KR + srow * KR_PB + sch * 16) = kreg; u32x2* d = (u32x2*)(lds + AL_VR + srow * VR_PB + sch * 16); u32x2 lo2, hi2; lo2.x = vreg.x; lo2.y = vreg.y; hi2.x = vreg.z; hi2.y = vreg.w; d[0] = lo2; d[1] = hi2; }
;       __syncthreads();
;       for (; j <= tb; ++j) { const bool hn = j + 1 <= tb;
;           if (hn) { kreg = *(const u32x4*)(kgb + (size_t)(64 * (j + 1)) * ZP * 2 + koff); vreg = *(const u32x4*)(vgb + (size_t)(64 * (j + 1)) * 2 + voff); }
;           if (64 * j + 63 >= t0 - 511 && 64 * j <= t0 + NTOK - 1)
;               attn_block64(st, qf, kfl + bi * KR_SZ, vfl + bi * VR_SZ, KR_PB, VR_PB, cref[2], true, (64 * j + 63 > t0) || (64 * j <= t0 + NTOK - 1 - 512), MaskWindow{tk[0]}, 64 * j, h);
	s_cbranch_scc1 .LBB0_111
	v_readlane_b32 s0, v254, 51
	s_add_i32 s11, s96, 0xfffffe01
	s_add_i32 s12, s96, 0xfffffe07
	s_sub_i32 s14, 0, s0
	s_sub_i32 s8, 0xe00, s0
	v_readlane_b32 s1, v254, 44
	v_readlane_b32 s9, v254, 55
	s_add_u32 s1, s1, s9
	v_readlane_b32 s9, v254, 45
	v_subrev_u32_e32 v151, s0, v154
	s_mul_i32 s0, s8, 0x2230
	s_addc_u32 s9, s9, 0
	s_add_u32 s0, s1, s0
	s_addc_u32 s1, s9, 0
	v_readlane_b32 s9, v254, 52
	s_add_u32 s0, s0, s9
	v_readlane_b32 s9, v254, 53
	s_addc_u32 s1, s1, s9
	v_lshl_add_u64 v[142:143], s[0:1], 0, v[142:143]
	v_readlane_b32 s0, v254, 56
	v_readlane_b32 s1, v254, 57
	v_readlane_b32 s2, v254, 48
	s_lshl_b64 s[0:1], s[0:1], 20
	s_lshl_b32 s9, s2, 19
	s_lshl_b32 s8, s8, 1
	v_readlane_b32 s15, v254, 46
	s_add_u32 s8, s15, s8
	v_readlane_b32 s15, v254, 47
	s_addc_u32 s15, s15, 0
	s_add_u32 s8, s8, s9
	v_mul_f32_e32 v0, v156, v157
	s_addc_u32 s9, s15, 0
	v_cmp_lt_f32_e32 vcc, s25, v0
	s_add_u32 s0, s8, s0
	v_mov_b32_e32 v137, 0
	v_cndmask_b32_e32 v32, 0, v0, vcc
	s_addc_u32 s1, s9, s1
	v_add_u32_e32 v147, 0xfffffe00, v136
	v_cmp_neq_f32_e64 s[6:7], 0, v32
	v_mov_b32_e32 v33, v32
	v_mov_b32_e32 v34, v32
	v_mov_b32_e32 v35, v32
	v_mov_b32_e32 v36, v32
	v_mov_b32_e32 v37, v32
	v_mov_b32_e32 v38, v32
	v_mov_b32_e32 v39, v32
	v_mov_b32_e32 v40, v32
	v_mov_b32_e32 v41, v32
	v_mov_b32_e32 v42, v32
	v_mov_b32_e32 v43, v32
	v_mov_b32_e32 v44, v32
	s_mov_b32 s13, 0
	v_lshl_add_u64 v[144:145], s[0:1], 0, v[160:161]
	s_mov_b32 s15, 0
	v_mov_b32_e32 v0, v137
	v_mov_b32_e32 v1, v137
	v_mov_b32_e32 v2, v137
	v_mov_b32_e32 v3, v137
	v_mov_b32_e32 v4, v137
	v_mov_b32_e32 v5, v137
	v_mov_b32_e32 v6, v137
	v_mov_b32_e32 v7, v137
	v_mov_b32_e32 v8, v137
	v_mov_b32_e32 v9, v137
	v_mov_b32_e32 v10, v137
	v_mov_b32_e32 v11, v137
	v_mov_b32_e32 v12, v137
	v_mov_b32_e32 v13, v137
	v_mov_b32_e32 v14, v137
	v_mov_b32_e32 v15, v137
	v_mov_b32_e32 v16, v137
	v_mov_b32_e32 v17, v137
	v_mov_b32_e32 v18, v137
	v_mov_b32_e32 v19, v137
	v_mov_b32_e32 v20, v137
	v_mov_b32_e32 v21, v137
	v_mov_b32_e32 v22, v137
	v_mov_b32_e32 v23, v137
	v_mov_b32_e32 v24, v137
	v_mov_b32_e32 v25, v137
	v_mov_b32_e32 v26, v137
	v_mov_b32_e32 v27, v137
	v_mov_b32_e32 v28, v137
	v_mov_b32_e32 v29, v137
	v_mov_b32_e32 v30, v137
	v_mov_b32_e32 v31, v137
	v_mov_b32_e32 v45, v32
	v_mov_b32_e32 v46, v32
	v_mov_b32_e32 v47, v32
	s_branch .LBB0_262
